# group-combine row loop software-pipelined: two rows of loads in flight (two register sets)
# baseline (speedup 1.0000x reference)
; __device__ __forceinline__ unsigned cvt_pk_bf16(float lo, float hi) { unsigned r; asm volatile("v_cvt_pk_bf16_f32 %0, %1, %2" : "=v"(r) : "v"(lo), "v"(hi)); return r; }
; __device__ __forceinline__ float bflo(unsigned w) { return __uint_as_float(w << 16); }
; __device__ __forceinline__ float bfhi(unsigned w) { return __uint_as_float(w & 0xffff0000u); }
; __device__ __forceinline__ void combine_row(const Args& a, size_t row, int lane) {
;     bf16_t* y = (bf16_t*)a.out + row * YP + 8 * lane; const bf16_t* o12 = (const bf16_t*)((unsigned char*)a.out + DO_O12) + row * 1024 + 8 * lane;
;     const float* lse = (const float*)(a.ws + WS_LSE) + row * 12; const int hh = lane >> 4;
;     const float l0 = lse[hh], l1 = lse[4 + hh], l2 = lse[8 + hh]; const float mx = fmaxf(l0, fmaxf(l1, l2));
;     float w0 = __expf(l0 - mx), w1 = __expf(l1 - mx), w2 = __expf(l2 - mx); const float inv = 1.0f / (w0 + w1 + w2); w0 *= inv; w1 *= inv; w2 *= inv;
;     const u32x4 v0 = *(const u32x4*)y, v1 = *(const u32x4*)o12, v2 = *(const u32x4*)(o12 + 512);
;     u32x4 w;
;     w.x = cvt_pk_bf16(w0 * bflo(v0.x) + w1 * bflo(v1.x) + w2 * bflo(v2.x), w0 * bfhi(v0.x) + w1 * bfhi(v1.x) + w2 * bfhi(v2.x));
;     w.y = cvt_pk_bf16(w0 * bflo(v0.y) + w1 * bflo(v1.y) + w2 * bflo(v2.y), w0 * bfhi(v0.y) + w1 * bfhi(v1.y) + w2 * bfhi(v2.y));
;     w.z = cvt_pk_bf16(w0 * bflo(v0.z) + w1 * bflo(v1.z) + w2 * bflo(v2.z), w0 * bfhi(v0.z) + w1 * bfhi(v1.z) + w2 * bfhi(v2.z));
;     w.w = cvt_pk_bf16(w0 * bflo(v0.w) + w1 * bflo(v1.w) + w2 * bflo(v2.w), w0 * bfhi(v0.w) + w1 * bfhi(v1.w) + w2 * bfhi(v2.w));
;     *(u32x4*)y = w;
; }
.LBB0_780:
	global_load_dword v26, v[0:1], off
	global_load_dword v27, v[0:1], off offset:16
	global_load_dword v28, v[0:1], off offset:32
	global_load_dwordx4 v[6:9], v[2:3], off
	global_load_dwordx4 v[10:13], v[4:5], off
	global_load_dwordx4 v[14:17], v[2:3], off offset:1024
	v_mov_b64_e32 v[250:251], v[4:5]
	s_add_i32 s6, s6, s94
	v_lshl_add_u64 v[0:1], v[0:1], 0, s[0:1]
	v_lshl_add_u64 v[2:3], v[2:3], 0, s[2:3]
	v_lshl_add_u64 v[4:5], v[4:5], 0, s[4:5]
	s_cmpk_gt_i32 s6, 0x3fff
	s_cbranch_scc1 .Lcmb_a_tailA
.Lcmb_a_loop:
	global_load_dword v232, v[0:1], off
	global_load_dword v233, v[0:1], off offset:16
	global_load_dword v234, v[0:1], off offset:32
	global_load_dwordx4 v[212:215], v[2:3], off
	global_load_dwordx4 v[216:219], v[4:5], off
	global_load_dwordx4 v[220:223], v[2:3], off offset:1024
	v_mov_b64_e32 v[252:253], v[4:5]
	s_add_i32 s6, s6, s94
	v_lshl_add_u64 v[0:1], v[0:1], 0, s[0:1]
	v_lshl_add_u64 v[2:3], v[2:3], 0, s[2:3]
	v_lshl_add_u64 v[4:5], v[4:5], 0, s[4:5]
	s_waitcnt vmcnt(6)
	v_max3_f32 v29, v26, v27, v28
	v_lshlrev_b32_e32 v32, 16, v7
	v_and_b32_e32 v33, 0xffff0000, v7
	v_lshlrev_b32_e32 v36, 16, v9
	v_lshlrev_b32_e32 v7, 16, v10
	v_and_b32_e32 v19, 0xffff0000, v10
	v_lshlrev_b32_e32 v20, 16, v15
	v_and_b32_e32 v10, 0xffff0000, v15
	v_lshlrev_b32_e32 v15, 16, v12
	v_and_b32_e32 v23, 0xffff0000, v12
	v_lshlrev_b32_e32 v25, 16, v13
	v_and_b32_e32 v37, 0xffff0000, v9
	v_and_b32_e32 v9, 0xffff0000, v13
	v_sub_f32_e32 v12, v26, v29
	v_sub_f32_e32 v13, v27, v29
	v_lshlrev_b32_e32 v30, 16, v6
	v_and_b32_e32 v31, 0xffff0000, v6
	v_lshlrev_b32_e32 v34, 16, v8
	v_and_b32_e32 v35, 0xffff0000, v8
	v_lshlrev_b32_e32 v6, 16, v14
	v_and_b32_e32 v18, 0xffff0000, v14
	v_lshlrev_b32_e32 v14, 16, v16
	v_and_b32_e32 v22, 0xffff0000, v16
	v_lshlrev_b32_e32 v24, 16, v17
	v_and_b32_e32 v8, 0xffff0000, v17
	v_sub_f32_e32 v16, v28, v29
	v_mul_f32_e32 v12, 0x3fb8aa3b, v12
	v_mul_f32_e32 v17, 0x3fb8aa3b, v13
	v_mul_f32_e32 v16, 0x3fb8aa3b, v16
	v_exp_f32_e32 v13, v12
	v_exp_f32_e32 v17, v17
	v_exp_f32_e32 v12, v16
	v_lshlrev_b32_e32 v21, 16, v11
	v_and_b32_e32 v11, 0xffff0000, v11
	v_add_f32_e32 v16, v13, v17
	v_add_f32_e32 v16, v12, v16
	v_div_scale_f32 v26, s[8:9], v16, v16, 1.0
	v_rcp_f32_e32 v28, v26
	v_div_scale_f32 v27, vcc, 1.0, v16, 1.0
	v_fma_f32 v29, -v26, v28, 1.0
	v_fmac_f32_e32 v28, v29, v28
	v_mul_f32_e32 v29, v27, v28
	v_fma_f32 v38, -v26, v29, v27
	v_fmac_f32_e32 v29, v38, v28
	v_fma_f32 v26, -v26, v29, v27
	v_div_fmas_f32 v26, v26, v28, v29
	v_div_fixup_f32 v16, v26, v16, 1.0
	v_pk_mul_f32 v[12:13], v[12:13], v[16:17] op_sel_hi:[1,0]
	v_mul_f32_e32 v26, v17, v16
	v_pk_mul_f32 v[6:7], v[12:13], v[6:7]
	v_pk_mul_f32 v[16:17], v[12:13], v[18:19]
	v_pk_mul_f32 v[8:9], v[12:13], v[8:9]
	v_pk_mul_f32 v[18:19], v[12:13], v[20:21]
	v_pk_mul_f32 v[10:11], v[12:13], v[10:11]
	v_pk_mul_f32 v[14:15], v[12:13], v[14:15]
	v_pk_mul_f32 v[20:21], v[12:13], v[22:23]
	v_pk_mul_f32 v[22:23], v[12:13], v[24:25]
	v_fma_f32 v7, v26, v30, v7
	v_fma_f32 v12, v26, v31, v17
	v_fma_f32 v9, v26, v37, v9
	v_fma_f32 v13, v26, v32, v19
	v_fma_f32 v11, v26, v33, v11
	v_fma_f32 v15, v26, v34, v15
	v_fma_f32 v17, v26, v35, v21
	v_fma_f32 v19, v26, v36, v23
	v_add_f32_e32 v6, v6, v7
	v_add_f32_e32 v7, v16, v12
	v_add_f32_e32 v9, v8, v9
	v_add_f32_e32 v12, v18, v13
	v_add_f32_e32 v10, v10, v11
	v_add_f32_e32 v11, v14, v15
	v_add_f32_e32 v13, v20, v17
	v_add_f32_e32 v14, v22, v19
	v_cvt_pk_bf16_f32 v6, v6, v7
	v_cvt_pk_bf16_f32 v7, v12, v10
	v_cvt_pk_bf16_f32 v8, v11, v13
	v_cvt_pk_bf16_f32 v9, v14, v9
	global_store_dwordx4 v[250:251], v[6:9], off
	s_cmpk_gt_i32 s6, 0x3fff
	s_cbranch_scc1 .Lcmb_a_tailB
	global_load_dword v26, v[0:1], off
	global_load_dword v27, v[0:1], off offset:16
	global_load_dword v28, v[0:1], off offset:32
	global_load_dwordx4 v[6:9], v[2:3], off
	global_load_dwordx4 v[10:13], v[4:5], off
	global_load_dwordx4 v[14:17], v[2:3], off offset:1024
	v_mov_b64_e32 v[250:251], v[4:5]
	s_add_i32 s6, s6, s94
	v_lshl_add_u64 v[0:1], v[0:1], 0, s[0:1]
	v_lshl_add_u64 v[2:3], v[2:3], 0, s[2:3]
	v_lshl_add_u64 v[4:5], v[4:5], 0, s[4:5]
	s_waitcnt vmcnt(6)
	v_max3_f32 v235, v232, v233, v234
	v_lshlrev_b32_e32 v238, 16, v213
	v_and_b32_e32 v239, 0xffff0000, v213
	v_lshlrev_b32_e32 v244, 16, v215
	v_lshlrev_b32_e32 v213, 16, v216
	v_and_b32_e32 v225, 0xffff0000, v216
	v_lshlrev_b32_e32 v226, 16, v221
	v_and_b32_e32 v216, 0xffff0000, v221
	v_lshlrev_b32_e32 v221, 16, v218
	v_and_b32_e32 v229, 0xffff0000, v218
	v_lshlrev_b32_e32 v231, 16, v219
	v_and_b32_e32 v245, 0xffff0000, v215
	v_and_b32_e32 v215, 0xffff0000, v219
	v_sub_f32_e32 v218, v232, v235
	v_sub_f32_e32 v219, v233, v235
	v_lshlrev_b32_e32 v236, 16, v212
	v_and_b32_e32 v237, 0xffff0000, v212
	v_lshlrev_b32_e32 v240, 16, v214
	v_and_b32_e32 v241, 0xffff0000, v214
	v_lshlrev_b32_e32 v212, 16, v220
	v_and_b32_e32 v224, 0xffff0000, v220
	v_lshlrev_b32_e32 v220, 16, v222
	v_and_b32_e32 v228, 0xffff0000, v222
	v_lshlrev_b32_e32 v230, 16, v223
	v_and_b32_e32 v214, 0xffff0000, v223
	v_sub_f32_e32 v222, v234, v235
	v_mul_f32_e32 v218, 0x3fb8aa3b, v218
	v_mul_f32_e32 v223, 0x3fb8aa3b, v219
	v_mul_f32_e32 v222, 0x3fb8aa3b, v222
	v_exp_f32_e32 v219, v218
	v_exp_f32_e32 v223, v223
	v_exp_f32_e32 v218, v222
	v_lshlrev_b32_e32 v227, 16, v217
	v_and_b32_e32 v217, 0xffff0000, v217
	v_add_f32_e32 v222, v219, v223
	v_add_f32_e32 v222, v218, v222
	v_div_scale_f32 v232, s[8:9], v222, v222, 1.0
	v_rcp_f32_e32 v234, v232
	v_div_scale_f32 v233, vcc, 1.0, v222, 1.0
	v_fma_f32 v235, -v232, v234, 1.0
	v_fmac_f32_e32 v234, v235, v234
	v_mul_f32_e32 v235, v233, v234
	v_fma_f32 v246, -v232, v235, v233
	v_fmac_f32_e32 v235, v246, v234
	v_fma_f32 v232, -v232, v235, v233
	v_div_fmas_f32 v232, v232, v234, v235
	v_div_fixup_f32 v222, v232, v222, 1.0
	v_pk_mul_f32 v[218:219], v[218:219], v[222:223] op_sel_hi:[1,0]
	v_mul_f32_e32 v232, v223, v222
	v_pk_mul_f32 v[212:213], v[218:219], v[212:213]
	v_pk_mul_f32 v[222:223], v[218:219], v[224:225]
	v_pk_mul_f32 v[214:215], v[218:219], v[214:215]
	v_pk_mul_f32 v[224:225], v[218:219], v[226:227]
	v_pk_mul_f32 v[216:217], v[218:219], v[216:217]
	v_pk_mul_f32 v[220:221], v[218:219], v[220:221]
	v_pk_mul_f32 v[226:227], v[218:219], v[228:229]
	v_pk_mul_f32 v[228:229], v[218:219], v[230:231]
	v_fma_f32 v213, v232, v236, v213
	v_fma_f32 v218, v232, v237, v223
	v_fma_f32 v215, v232, v245, v215
	v_fma_f32 v219, v232, v238, v225
	v_fma_f32 v217, v232, v239, v217
	v_fma_f32 v221, v232, v240, v221
	v_fma_f32 v223, v232, v241, v227
	v_fma_f32 v225, v232, v244, v229
	v_add_f32_e32 v212, v212, v213
	v_add_f32_e32 v213, v222, v218
	v_add_f32_e32 v215, v214, v215
	v_add_f32_e32 v218, v224, v219
	v_add_f32_e32 v216, v216, v217
	v_add_f32_e32 v217, v220, v221
	v_add_f32_e32 v219, v226, v223
	v_add_f32_e32 v220, v228, v225
	v_cvt_pk_bf16_f32 v212, v212, v213
	v_cvt_pk_bf16_f32 v213, v218, v216
	v_cvt_pk_bf16_f32 v214, v217, v219
	v_cvt_pk_bf16_f32 v215, v220, v215
	global_store_dwordx4 v[252:253], v[212:215], off
	s_cmpk_gt_i32 s6, 0x3fff
	s_cbranch_scc0 .Lcmb_a_loop
; __device__ __forceinline__ unsigned cvt_pk_bf16(float lo, float hi) { unsigned r; asm volatile("v_cvt_pk_bf16_f32 %0, %1, %2" : "=v"(r) : "v"(lo), "v"(hi)); return r; }
; __device__ __forceinline__ float bflo(unsigned w) { return __uint_as_float(w << 16); }
; __device__ __forceinline__ float bfhi(unsigned w) { return __uint_as_float(w & 0xffff0000u); }
; __device__ __forceinline__ void combine_row(const Args& a, size_t row, int lane) {
;     bf16_t* y = (bf16_t*)a.out + row * YP + 8 * lane; const bf16_t* o12 = (const bf16_t*)((unsigned char*)a.out + DO_O12) + row * 1024 + 8 * lane;
;     const float* lse = (const float*)(a.ws + WS_LSE) + row * 12; const int hh = lane >> 4;
;     const float l0 = lse[hh], l1 = lse[4 + hh], l2 = lse[8 + hh]; const float mx = fmaxf(l0, fmaxf(l1, l2));
;     float w0 = __expf(l0 - mx), w1 = __expf(l1 - mx), w2 = __expf(l2 - mx); const float inv = 1.0f / (w0 + w1 + w2); w0 *= inv; w1 *= inv; w2 *= inv;
;     const u32x4 v0 = *(const u32x4*)y, v1 = *(const u32x4*)o12, v2 = *(const u32x4*)(o12 + 512);
;     u32x4 w;
;     w.x = cvt_pk_bf16(w0 * bflo(v0.x) + w1 * bflo(v1.x) + w2 * bflo(v2.x), w0 * bfhi(v0.x) + w1 * bfhi(v1.x) + w2 * bfhi(v2.x));
;     w.y = cvt_pk_bf16(w0 * bflo(v0.y) + w1 * bflo(v1.y) + w2 * bflo(v2.y), w0 * bfhi(v0.y) + w1 * bfhi(v1.y) + w2 * bfhi(v2.y));
;     w.z = cvt_pk_bf16(w0 * bflo(v0.z) + w1 * bflo(v1.z) + w2 * bflo(v2.z), w0 * bfhi(v0.z) + w1 * bfhi(v1.z) + w2 * bfhi(v2.z));
;     w.w = cvt_pk_bf16(w0 * bflo(v0.w) + w1 * bflo(v1.w) + w2 * bflo(v2.w), w0 * bfhi(v0.w) + w1 * bfhi(v1.w) + w2 * bfhi(v2.w));
;     *(u32x4*)y = w;
; }
.Lcmb_a_tailA:
	s_waitcnt vmcnt(0)
	v_max3_f32 v29, v26, v27, v28
	v_lshlrev_b32_e32 v32, 16, v7
	v_and_b32_e32 v33, 0xffff0000, v7
	v_lshlrev_b32_e32 v36, 16, v9
	v_lshlrev_b32_e32 v7, 16, v10
	v_and_b32_e32 v19, 0xffff0000, v10
	v_lshlrev_b32_e32 v20, 16, v15
	v_and_b32_e32 v10, 0xffff0000, v15
	v_lshlrev_b32_e32 v15, 16, v12
	v_and_b32_e32 v23, 0xffff0000, v12
	v_lshlrev_b32_e32 v25, 16, v13
	v_and_b32_e32 v37, 0xffff0000, v9
	v_and_b32_e32 v9, 0xffff0000, v13
	v_sub_f32_e32 v12, v26, v29
	v_sub_f32_e32 v13, v27, v29
	v_lshlrev_b32_e32 v30, 16, v6
	v_and_b32_e32 v31, 0xffff0000, v6
	v_lshlrev_b32_e32 v34, 16, v8
	v_and_b32_e32 v35, 0xffff0000, v8
	v_lshlrev_b32_e32 v6, 16, v14
	v_and_b32_e32 v18, 0xffff0000, v14
	v_lshlrev_b32_e32 v14, 16, v16
	v_and_b32_e32 v22, 0xffff0000, v16
	v_lshlrev_b32_e32 v24, 16, v17
	v_and_b32_e32 v8, 0xffff0000, v17
	v_sub_f32_e32 v16, v28, v29
	v_mul_f32_e32 v12, 0x3fb8aa3b, v12
	v_mul_f32_e32 v17, 0x3fb8aa3b, v13
	v_mul_f32_e32 v16, 0x3fb8aa3b, v16
	v_exp_f32_e32 v13, v12
	v_exp_f32_e32 v17, v17
	v_exp_f32_e32 v12, v16
	v_lshlrev_b32_e32 v21, 16, v11
	v_and_b32_e32 v11, 0xffff0000, v11
	v_add_f32_e32 v16, v13, v17
	v_add_f32_e32 v16, v12, v16
	v_div_scale_f32 v26, s[8:9], v16, v16, 1.0
	v_rcp_f32_e32 v28, v26
	v_div_scale_f32 v27, vcc, 1.0, v16, 1.0
	v_fma_f32 v29, -v26, v28, 1.0
	v_fmac_f32_e32 v28, v29, v28
	v_mul_f32_e32 v29, v27, v28
	v_fma_f32 v38, -v26, v29, v27
	v_fmac_f32_e32 v29, v38, v28
	v_fma_f32 v26, -v26, v29, v27
	v_div_fmas_f32 v26, v26, v28, v29
	v_div_fixup_f32 v16, v26, v16, 1.0
	v_pk_mul_f32 v[12:13], v[12:13], v[16:17] op_sel_hi:[1,0]
	v_mul_f32_e32 v26, v17, v16
	v_pk_mul_f32 v[6:7], v[12:13], v[6:7]
	v_pk_mul_f32 v[16:17], v[12:13], v[18:19]
	v_pk_mul_f32 v[8:9], v[12:13], v[8:9]
	v_pk_mul_f32 v[18:19], v[12:13], v[20:21]
	v_pk_mul_f32 v[10:11], v[12:13], v[10:11]
	v_pk_mul_f32 v[14:15], v[12:13], v[14:15]
	v_pk_mul_f32 v[20:21], v[12:13], v[22:23]
	v_pk_mul_f32 v[22:23], v[12:13], v[24:25]
	v_fma_f32 v7, v26, v30, v7
	v_fma_f32 v12, v26, v31, v17
	v_fma_f32 v9, v26, v37, v9
	v_fma_f32 v13, v26, v32, v19
	v_fma_f32 v11, v26, v33, v11
	v_fma_f32 v15, v26, v34, v15
	v_fma_f32 v17, v26, v35, v21
	v_fma_f32 v19, v26, v36, v23
	v_add_f32_e32 v6, v6, v7
	v_add_f32_e32 v7, v16, v12
	v_add_f32_e32 v9, v8, v9
	v_add_f32_e32 v12, v18, v13
	v_add_f32_e32 v10, v10, v11
	v_add_f32_e32 v11, v14, v15
	v_add_f32_e32 v13, v20, v17
	v_add_f32_e32 v14, v22, v19
	v_cvt_pk_bf16_f32 v6, v6, v7
	v_cvt_pk_bf16_f32 v7, v12, v10
	v_cvt_pk_bf16_f32 v8, v11, v13
	v_cvt_pk_bf16_f32 v9, v14, v9
	global_store_dwordx4 v[250:251], v[6:9], off
	s_branch .Lcmb_a_end
.Lcmb_a_tailB:
	s_waitcnt vmcnt(0)
	v_max3_f32 v235, v232, v233, v234
	v_lshlrev_b32_e32 v238, 16, v213
	v_and_b32_e32 v239, 0xffff0000, v213
	v_lshlrev_b32_e32 v244, 16, v215
	v_lshlrev_b32_e32 v213, 16, v216
	v_and_b32_e32 v225, 0xffff0000, v216
	v_lshlrev_b32_e32 v226, 16, v221
	v_and_b32_e32 v216, 0xffff0000, v221
	v_lshlrev_b32_e32 v221, 16, v218
	v_and_b32_e32 v229, 0xffff0000, v218
	v_lshlrev_b32_e32 v231, 16, v219
	v_and_b32_e32 v245, 0xffff0000, v215
	v_and_b32_e32 v215, 0xffff0000, v219
	v_sub_f32_e32 v218, v232, v235
	v_sub_f32_e32 v219, v233, v235
	v_lshlrev_b32_e32 v236, 16, v212
	v_and_b32_e32 v237, 0xffff0000, v212
	v_lshlrev_b32_e32 v240, 16, v214
	v_and_b32_e32 v241, 0xffff0000, v214
	v_lshlrev_b32_e32 v212, 16, v220
	v_and_b32_e32 v224, 0xffff0000, v220
	v_lshlrev_b32_e32 v220, 16, v222
	v_and_b32_e32 v228, 0xffff0000, v222
	v_lshlrev_b32_e32 v230, 16, v223
	v_and_b32_e32 v214, 0xffff0000, v223
	v_sub_f32_e32 v222, v234, v235
	v_mul_f32_e32 v218, 0x3fb8aa3b, v218
	v_mul_f32_e32 v223, 0x3fb8aa3b, v219
	v_mul_f32_e32 v222, 0x3fb8aa3b, v222
	v_exp_f32_e32 v219, v218
	v_exp_f32_e32 v223, v223
	v_exp_f32_e32 v218, v222
	v_lshlrev_b32_e32 v227, 16, v217
	v_and_b32_e32 v217, 0xffff0000, v217
	v_add_f32_e32 v222, v219, v223
	v_add_f32_e32 v222, v218, v222
	v_div_scale_f32 v232, s[8:9], v222, v222, 1.0
	v_rcp_f32_e32 v234, v232
	v_div_scale_f32 v233, vcc, 1.0, v222, 1.0
	v_fma_f32 v235, -v232, v234, 1.0
	v_fmac_f32_e32 v234, v235, v234
	v_mul_f32_e32 v235, v233, v234
	v_fma_f32 v246, -v232, v235, v233
	v_fmac_f32_e32 v235, v246, v234
	v_fma_f32 v232, -v232, v235, v233
	v_div_fmas_f32 v232, v232, v234, v235
	v_div_fixup_f32 v222, v232, v222, 1.0
	v_pk_mul_f32 v[218:219], v[218:219], v[222:223] op_sel_hi:[1,0]
	v_mul_f32_e32 v232, v223, v222
	v_pk_mul_f32 v[212:213], v[218:219], v[212:213]
	v_pk_mul_f32 v[222:223], v[218:219], v[224:225]
	v_pk_mul_f32 v[214:215], v[218:219], v[214:215]
	v_pk_mul_f32 v[224:225], v[218:219], v[226:227]
	v_pk_mul_f32 v[216:217], v[218:219], v[216:217]
	v_pk_mul_f32 v[220:221], v[218:219], v[220:221]
	v_pk_mul_f32 v[226:227], v[218:219], v[228:229]
	v_pk_mul_f32 v[228:229], v[218:219], v[230:231]
	v_fma_f32 v213, v232, v236, v213
	v_fma_f32 v218, v232, v237, v223
	v_fma_f32 v215, v232, v245, v215
	v_fma_f32 v219, v232, v238, v225
	v_fma_f32 v217, v232, v239, v217
	v_fma_f32 v221, v232, v240, v221
	v_fma_f32 v223, v232, v241, v227
	v_fma_f32 v225, v232, v244, v229
	v_add_f32_e32 v212, v212, v213
	v_add_f32_e32 v213, v222, v218
	v_add_f32_e32 v215, v214, v215
	v_add_f32_e32 v218, v224, v219
	v_add_f32_e32 v216, v216, v217
	v_add_f32_e32 v217, v220, v221
	v_add_f32_e32 v219, v226, v223
	v_add_f32_e32 v220, v228, v225
	v_cvt_pk_bf16_f32 v212, v212, v213
	v_cvt_pk_bf16_f32 v213, v218, v216
	v_cvt_pk_bf16_f32 v214, v217, v219
	v_cvt_pk_bf16_f32 v215, v220, v215
	global_store_dwordx4 v[252:253], v[212:215], off
; #define PG8_STAGE(bufoff, gbase, voff) do { _Pragma("unroll") for (int _i = 0; _i < 2; ++_i) \
;         __builtin_amdgcn_global_load_lds((const unsigned*)((const char*)(gbase) + (voff)[_i]), (LAS unsigned*)(lds + (bufoff) + ldsw + _i * 8192), 16, 0, 0); } while (0)
; #define PG8_WAIT_V(n) asm volatile("s_waitcnt vmcnt(" #n ")" ::: "memory")
; #define PG8_BAR __builtin_amdgcn_s_barrier()
; template <class Epi, class Sched, bool ALIGN_EPI = true>
; __device__ __forceinline__ void gemm_phase(LAS unsigned char* lds, const Gemm g, const Sched& S, const Epi& E) {
;     ...
;     for (int i = 0; i < 2; ++i) { int R, C; stage_rc(tid * 16 + i * 8192, R, C); const int Rb = Epi::PERM ? ((R & ~31) + perm32(R & 31)) : R;
;         voffA[i] = (unsigned)(R * g.lda + C) * 2u; voffB[i] = (unsigned)(Rb * g.ldb + C) * 2u; }
;     const size_t kstep = (size_t)(BK * 2);
;     const size_t hstepA = (size_t)HALF * g.lda * 2, hstepB = (size_t)HALF * g.ldb * 2;
;     const size_t tstepA = 2 * hstepA, tstepB = 2 * hstepB;
;     const unsigned ldsw = (unsigned)wid * 1024u;
;     const int aoff = lds_byte(wr * 64 + fr, fq * 8), boff = lds_byte(wc * 32 + fr, fq * 8);
;     ...
;     const char* cA = (const char*)g.A + (size_t)cur.pm * tstepA; const char* cB = (const char*)g.Bt + (size_t)cur.pn * tstepB;
;     PG8_STAGE(PG8_SB(0, 0), cB, voffB); PG8_STAGE(PG8_SB(0, 1), cB + hstepB, voffB); PG8_STAGE(PG8_SA(0, 0), cA, voffA); PG8_STAGE(PG8_SA(0, 1), cA + hstepA, voffA);
;     if (wr == 1) PG8_BAR;
;     PG8_WAIT_V(2); PG8_BAR;
;     PG8_STAGE(PG8_SB(1, 0), cB + kstep, voffB); PG8_STAGE(PG8_SA(1, 0), cA + kstep, voffA); PG8_STAGE(PG8_SB(1, 1), cB + hstepB + kstep, voffB);
;     PG8_WAIT_V(6); PG8_BAR;
.Lcmb_a_end:
.LBB0_781:
	s_cmpk_gt_u32 s96, 0x5ff
	v_readfirstlane_b32 s0, v144
	v_readlane_b32 s97, v242, 39
	s_waitcnt vmcnt(0)
	s_barrier
	s_cbranch_scc1 .LBB0_797
	v_lshrrev_b32_e32 v0, 5, v144
	v_lshrrev_b32_e32 v2, 1, v144
	v_and_b32_e32 v0, 4, v0
	v_bfe_u32 v1, v144, 2, 2
	v_and_b32_e32 v11, 24, v2
	v_or3_b32 v0, v0, v1, v11
	v_lshlrev_b32_e32 v1, 4, v144
	v_add_u32_e32 v8, 0x2000, v1
	v_lshrrev_b32_e32 v2, 7, v8
	s_movk_i32 s2, 0xe0
	v_and_b32_e32 v4, 32, v144
	v_and_or_b32 v3, v2, s2, v0
	v_bitop3_b32 v9, v1, v4, 48 bitop3:0x6c
	v_and_b32_e32 v10, 64, v144
	v_bfe_u32 v12, v144, 2, 4
	s_movk_i32 s2, 0xf0
	s_add_u32 s38, s22, 0xa400000
	v_or_b32_e32 v1, v9, v10
	v_and_or_b32 v2, v2, s2, v12
	s_addc_u32 s39, s23, 0
	v_lshl_or_b32 v148, v2, 12, v1
	v_lshrrev_b32_e32 v2, 3, v144
	s_movk_i32 s2, 0x60
	s_add_u32 s40, s22, 0x3000000
	v_and_or_b32 v0, v2, s2, v0
	s_movk_i32 s2, 0x70
	s_addc_u32 s41, s23, 0
	v_lshl_or_b32 v150, v0, 12, v1
	v_and_or_b32 v0, v2, s2, v12
	s_and_b32 s2, s96, 7
	s_lshr_b32 s3, s96, 3
	s_mulk_i32 s2, 0xc0
	s_add_i32 s2, s2, s3
	s_mul_i32 s3, s2, 0xaaab
	s_lshr_b32 s3, s3, 23
	s_lshl_b32 s4, s3, 3
	s_mulk_i32 s3, 0xc0
	s_sub_i32 s2, s2, s3
	s_and_b32 s3, s2, 7
	s_lshr_b32 s6, s0, 6
	s_or_b32 s8, s3, s4
	s_bfe_u32 s9, s2, 0xd0003
	s_lshr_b32 s1, s0, 8
	s_lshl_b32 s42, s6, 10
	s_lshl_b32 s7, s8, 20
	s_lshl_b32 s2, s9, 20
	s_add_u32 s4, s40, s2
	s_addc_u32 s5, s41, 0
	s_add_i32 s43, s42, 0
	s_add_i32 m0, s43, 0x10000
	v_lshl_or_b32 v146, v3, 12, v1
	global_load_lds_dwordx4 v150, s[4:5]
	s_add_i32 m0, s43, 0x12000
	s_add_u32 s2, s4, 0x80000
	global_load_lds_dwordx4 v146, s[4:5]
	s_addc_u32 s3, s5, 0
	s_add_i32 m0, s43, 0x14000
	v_lshl_or_b32 v152, v0, 12, v1
	global_load_lds_dwordx4 v150, s[2:3]
	s_add_i32 m0, s43, 0x16000
	v_mov_b32_e32 v151, 0
	global_load_lds_dwordx4 v146, s[2:3]
	s_add_u32 s2, s38, s7
	s_addc_u32 s3, s39, 0
	s_add_i32 s44, s43, 0x2000
	s_mov_b32 m0, s43
	s_add_u32 s10, s2, 0x80000
	global_load_lds_dwordx4 v152, s[2:3]
	s_mov_b32 m0, s44
	s_addc_u32 s11, s3, 0
	s_add_i32 s45, s43, 0x4000
	global_load_lds_dwordx4 v148, s[2:3]
	s_mov_b32 m0, s45
	s_add_i32 s46, s43, 0x6000
	global_load_lds_dwordx4 v152, s[10:11]
	s_mov_b32 m0, s46
	v_mov_b32_e32 v147, v151
	global_load_lds_dwordx4 v148, s[10:11]
	v_mov_b32_e32 v153, v151
	v_mov_b32_e32 v149, v151
	s_cmp_eq_u32 s1, 1
	s_mov_b32 s47, 0
	v_lshl_add_u64 v[6:7], s[4:5], 0, v[150:151]
	v_lshl_add_u64 v[4:5], s[4:5], 0, v[146:147]
	v_lshl_add_u64 v[0:1], s[2:3], 0, v[152:153]
	s_cselect_b64 s[10:11], -1, 0
	s_cmp_lg_u32 s1, 1
	v_lshl_add_u64 v[2:3], s[2:3], 0, v[148:149]
	s_cbranch_scc1 .LBB0_784
	s_barrier

; __device__ __forceinline__ unsigned cvt_pk_bf16(float lo, float hi) { unsigned r; asm volatile("v_cvt_pk_bf16_f32 %0, %1, %2" : "=v"(r) : "v"(lo), "v"(hi)); return r; }
; __device__ __forceinline__ float bflo(unsigned w) { return __uint_as_float(w << 16); }
; __device__ __forceinline__ float bfhi(unsigned w) { return __uint_as_float(w & 0xffff0000u); }
; __device__ __forceinline__ void combine_row(const Args& a, size_t row, int lane) {
;     bf16_t* y = (bf16_t*)a.out + row * YP + 8 * lane; const bf16_t* o12 = (const bf16_t*)((unsigned char*)a.out + DO_O12) + row * 1024 + 8 * lane;
;     const float* lse = (const float*)(a.ws + WS_LSE) + row * 12; const int hh = lane >> 4;
;     const float l0 = lse[hh], l1 = lse[4 + hh], l2 = lse[8 + hh]; const float mx = fmaxf(l0, fmaxf(l1, l2));
;     float w0 = __expf(l0 - mx), w1 = __expf(l1 - mx), w2 = __expf(l2 - mx); const float inv = 1.0f / (w0 + w1 + w2); w0 *= inv; w1 *= inv; w2 *= inv;
;     const u32x4 v0 = *(const u32x4*)y, v1 = *(const u32x4*)o12, v2 = *(const u32x4*)(o12 + 512);
;     u32x4 w;
;     w.x = cvt_pk_bf16(w0 * bflo(v0.x) + w1 * bflo(v1.x) + w2 * bflo(v2.x), w0 * bfhi(v0.x) + w1 * bfhi(v1.x) + w2 * bfhi(v2.x));
;     w.y = cvt_pk_bf16(w0 * bflo(v0.y) + w1 * bflo(v1.y) + w2 * bflo(v2.y), w0 * bfhi(v0.y) + w1 * bfhi(v1.y) + w2 * bfhi(v2.y));
;     w.z = cvt_pk_bf16(w0 * bflo(v0.z) + w1 * bflo(v1.z) + w2 * bflo(v2.z), w0 * bfhi(v0.z) + w1 * bfhi(v1.z) + w2 * bfhi(v2.z));
;     w.w = cvt_pk_bf16(w0 * bflo(v0.w) + w1 * bflo(v1.w) + w2 * bflo(v2.w), w0 * bfhi(v0.w) + w1 * bfhi(v1.w) + w2 * bfhi(v2.w));
;     *(u32x4*)y = w;
; }
.Lcmb_b_loop:
	global_load_dword v232, v[0:1], off
	global_load_dword v233, v[0:1], off offset:16
	global_load_dword v234, v[0:1], off offset:32
	global_load_dwordx4 v[212:215], v[2:3], off
	global_load_dwordx4 v[216:219], v[4:5], off
	global_load_dwordx4 v[220:223], v[2:3], off offset:1024
	v_mov_b64_e32 v[252:253], v[4:5]
	s_add_i32 s6, s6, s94
	v_lshl_add_u64 v[0:1], v[0:1], 0, s[0:1]
	v_lshl_add_u64 v[2:3], v[2:3], 0, s[2:3]
	v_lshl_add_u64 v[4:5], v[4:5], 0, s[4:5]
	s_waitcnt vmcnt(9)
	v_max3_f32 v29, v26, v27, v28
	s_waitcnt vmcnt(8)
	v_lshlrev_b32_e32 v32, 16, v7
	v_and_b32_e32 v33, 0xffff0000, v7
	v_lshlrev_b32_e32 v36, 16, v9
	s_waitcnt vmcnt(7)
	v_lshlrev_b32_e32 v7, 16, v10
	v_and_b32_e32 v19, 0xffff0000, v10
	s_waitcnt vmcnt(6)
	v_lshlrev_b32_e32 v20, 16, v15
	v_and_b32_e32 v10, 0xffff0000, v15
	v_lshlrev_b32_e32 v15, 16, v12
	v_and_b32_e32 v23, 0xffff0000, v12
	v_lshlrev_b32_e32 v25, 16, v13
	v_and_b32_e32 v37, 0xffff0000, v9
	v_and_b32_e32 v9, 0xffff0000, v13
	v_sub_f32_e32 v12, v26, v29
	v_sub_f32_e32 v13, v27, v29
	v_lshlrev_b32_e32 v30, 16, v6
	v_and_b32_e32 v31, 0xffff0000, v6
	v_lshlrev_b32_e32 v34, 16, v8
	v_and_b32_e32 v35, 0xffff0000, v8
	v_lshlrev_b32_e32 v6, 16, v14
	v_and_b32_e32 v18, 0xffff0000, v14
	v_lshlrev_b32_e32 v14, 16, v16
	v_and_b32_e32 v22, 0xffff0000, v16
	v_lshlrev_b32_e32 v24, 16, v17
	v_and_b32_e32 v8, 0xffff0000, v17
	v_sub_f32_e32 v16, v28, v29
	v_mul_f32_e32 v12, 0x3fb8aa3b, v12
	v_mul_f32_e32 v17, 0x3fb8aa3b, v13
	v_mul_f32_e32 v16, 0x3fb8aa3b, v16
	v_exp_f32_e32 v13, v12
	v_exp_f32_e32 v17, v17
	v_exp_f32_e32 v12, v16
	v_lshlrev_b32_e32 v21, 16, v11
	v_and_b32_e32 v11, 0xffff0000, v11
	v_add_f32_e32 v16, v13, v17
	v_add_f32_e32 v16, v12, v16
	v_div_scale_f32 v26, s[8:9], v16, v16, 1.0
	v_rcp_f32_e32 v28, v26
	v_div_scale_f32 v27, vcc, 1.0, v16, 1.0
	v_fma_f32 v29, -v26, v28, 1.0
	v_fmac_f32_e32 v28, v29, v28
	v_mul_f32_e32 v29, v27, v28
	v_fma_f32 v38, -v26, v29, v27
	v_fmac_f32_e32 v29, v38, v28
	v_fma_f32 v26, -v26, v29, v27
	v_div_fmas_f32 v26, v26, v28, v29
	v_div_fixup_f32 v16, v26, v16, 1.0
	v_pk_mul_f32 v[12:13], v[12:13], v[16:17] op_sel_hi:[1,0]
	v_mul_f32_e32 v26, v17, v16
	v_pk_mul_f32 v[6:7], v[12:13], v[6:7]
	v_pk_mul_f32 v[16:17], v[12:13], v[18:19]
	v_pk_mul_f32 v[8:9], v[12:13], v[8:9]
	v_pk_mul_f32 v[18:19], v[12:13], v[20:21]
	v_pk_mul_f32 v[10:11], v[12:13], v[10:11]
	v_pk_mul_f32 v[14:15], v[12:13], v[14:15]
	v_pk_mul_f32 v[20:21], v[12:13], v[22:23]
	v_pk_mul_f32 v[22:23], v[12:13], v[24:25]
	v_fma_f32 v7, v26, v30, v7
	v_fma_f32 v12, v26, v31, v17
	v_fma_f32 v9, v26, v37, v9
	v_fma_f32 v13, v26, v32, v19
	v_fma_f32 v11, v26, v33, v11
	v_fma_f32 v15, v26, v34, v15
	v_fma_f32 v17, v26, v35, v21
	v_fma_f32 v19, v26, v36, v23
	v_add_f32_e32 v6, v6, v7
	v_add_f32_e32 v7, v16, v12
	v_add_f32_e32 v9, v8, v9
	v_add_f32_e32 v12, v18, v13
	v_add_f32_e32 v10, v10, v11
	v_add_f32_e32 v11, v14, v15
	v_add_f32_e32 v13, v20, v17
	v_add_f32_e32 v14, v22, v19
	v_cvt_pk_bf16_f32 v6, v6, v7
	v_cvt_pk_bf16_f32 v7, v12, v10
	v_cvt_pk_bf16_f32 v8, v11, v13
	v_cvt_pk_bf16_f32 v9, v14, v9
	global_store_dwordx4 v[250:251], v[6:9], off
	s_cmpk_gt_i32 s6, 0x3fff
	s_cbranch_scc1 .Lcmb_b_tailB
	global_load_dword v26, v[0:1], off
	global_load_dword v27, v[0:1], off offset:16
	global_load_dword v28, v[0:1], off offset:32
	global_load_dwordx4 v[6:9], v[2:3], off
	global_load_dwordx4 v[10:13], v[4:5], off
	global_load_dwordx4 v[14:17], v[2:3], off offset:1024
	v_mov_b64_e32 v[250:251], v[4:5]
	s_add_i32 s6, s6, s94
	v_lshl_add_u64 v[0:1], v[0:1], 0, s[0:1]
	v_lshl_add_u64 v[2:3], v[2:3], 0, s[2:3]
	v_lshl_add_u64 v[4:5], v[4:5], 0, s[4:5]
	s_waitcnt vmcnt(9)
	v_max3_f32 v235, v232, v233, v234
	s_waitcnt vmcnt(8)
	v_lshlrev_b32_e32 v238, 16, v213
	v_and_b32_e32 v239, 0xffff0000, v213
	v_lshlrev_b32_e32 v244, 16, v215
	s_waitcnt vmcnt(7)
	v_lshlrev_b32_e32 v213, 16, v216
	v_and_b32_e32 v225, 0xffff0000, v216
	s_waitcnt vmcnt(6)
	v_lshlrev_b32_e32 v226, 16, v221
	v_and_b32_e32 v216, 0xffff0000, v221
	v_lshlrev_b32_e32 v221, 16, v218
	v_and_b32_e32 v229, 0xffff0000, v218
	v_lshlrev_b32_e32 v231, 16, v219
	v_and_b32_e32 v245, 0xffff0000, v215
	v_and_b32_e32 v215, 0xffff0000, v219
	v_sub_f32_e32 v218, v232, v235
	v_sub_f32_e32 v219, v233, v235
	v_lshlrev_b32_e32 v236, 16, v212
	v_and_b32_e32 v237, 0xffff0000, v212
	v_lshlrev_b32_e32 v240, 16, v214
	v_and_b32_e32 v241, 0xffff0000, v214
	v_lshlrev_b32_e32 v212, 16, v220
	v_and_b32_e32 v224, 0xffff0000, v220
	v_lshlrev_b32_e32 v220, 16, v222
	v_and_b32_e32 v228, 0xffff0000, v222
	v_lshlrev_b32_e32 v230, 16, v223
	v_and_b32_e32 v214, 0xffff0000, v223
	v_sub_f32_e32 v222, v234, v235
	v_mul_f32_e32 v218, 0x3fb8aa3b, v218
	v_mul_f32_e32 v223, 0x3fb8aa3b, v219
	v_mul_f32_e32 v222, 0x3fb8aa3b, v222
	v_exp_f32_e32 v219, v218
	v_exp_f32_e32 v223, v223
	v_exp_f32_e32 v218, v222
	v_lshlrev_b32_e32 v227, 16, v217
	v_and_b32_e32 v217, 0xffff0000, v217
	v_add_f32_e32 v222, v219, v223
	v_add_f32_e32 v222, v218, v222
	v_div_scale_f32 v232, s[8:9], v222, v222, 1.0
	v_rcp_f32_e32 v234, v232
	v_div_scale_f32 v233, vcc, 1.0, v222, 1.0
	v_fma_f32 v235, -v232, v234, 1.0
	v_fmac_f32_e32 v234, v235, v234
	v_mul_f32_e32 v235, v233, v234
	v_fma_f32 v246, -v232, v235, v233
	v_fmac_f32_e32 v235, v246, v234
	v_fma_f32 v232, -v232, v235, v233
	v_div_fmas_f32 v232, v232, v234, v235
	v_div_fixup_f32 v222, v232, v222, 1.0
	v_pk_mul_f32 v[218:219], v[218:219], v[222:223] op_sel_hi:[1,0]
	v_mul_f32_e32 v232, v223, v222
	v_pk_mul_f32 v[212:213], v[218:219], v[212:213]
	v_pk_mul_f32 v[222:223], v[218:219], v[224:225]
	v_pk_mul_f32 v[214:215], v[218:219], v[214:215]
	v_pk_mul_f32 v[224:225], v[218:219], v[226:227]
	v_pk_mul_f32 v[216:217], v[218:219], v[216:217]
	v_pk_mul_f32 v[220:221], v[218:219], v[220:221]
	v_pk_mul_f32 v[226:227], v[218:219], v[228:229]
	v_pk_mul_f32 v[228:229], v[218:219], v[230:231]
	v_fma_f32 v213, v232, v236, v213
	v_fma_f32 v218, v232, v237, v223
	v_fma_f32 v215, v232, v245, v215
	v_fma_f32 v219, v232, v238, v225
	v_fma_f32 v217, v232, v239, v217
	v_fma_f32 v221, v232, v240, v221
	v_fma_f32 v223, v232, v241, v227
	v_fma_f32 v225, v232, v244, v229
	v_add_f32_e32 v212, v212, v213
	v_add_f32_e32 v213, v222, v218
	v_add_f32_e32 v215, v214, v215
	v_add_f32_e32 v218, v224, v219
	v_add_f32_e32 v216, v216, v217
	v_add_f32_e32 v217, v220, v221
	v_add_f32_e32 v219, v226, v223
	v_add_f32_e32 v220, v228, v225
	v_cvt_pk_bf16_f32 v212, v212, v213
	v_cvt_pk_bf16_f32 v213, v218, v216
	v_cvt_pk_bf16_f32 v214, v217, v219
	v_cvt_pk_bf16_f32 v215, v220, v215
	global_store_dwordx4 v[252:253], v[212:215], off
	s_cmpk_gt_i32 s6, 0x3fff
	s_cbranch_scc0 .Lcmb_b_loop
; __device__ __forceinline__ unsigned cvt_pk_bf16(float lo, float hi) { unsigned r; asm volatile("v_cvt_pk_bf16_f32 %0, %1, %2" : "=v"(r) : "v"(lo), "v"(hi)); return r; }
; __device__ __forceinline__ float bflo(unsigned w) { return __uint_as_float(w << 16); }
; __device__ __forceinline__ float bfhi(unsigned w) { return __uint_as_float(w & 0xffff0000u); }
; __device__ __forceinline__ void combine_row(const Args& a, size_t row, int lane) {
;     bf16_t* y = (bf16_t*)a.out + row * YP + 8 * lane; const bf16_t* o12 = (const bf16_t*)((unsigned char*)a.out + DO_O12) + row * 1024 + 8 * lane;
;     const float* lse = (const float*)(a.ws + WS_LSE) + row * 12; const int hh = lane >> 4;
;     const float l0 = lse[hh], l1 = lse[4 + hh], l2 = lse[8 + hh]; const float mx = fmaxf(l0, fmaxf(l1, l2));
;     float w0 = __expf(l0 - mx), w1 = __expf(l1 - mx), w2 = __expf(l2 - mx); const float inv = 1.0f / (w0 + w1 + w2); w0 *= inv; w1 *= inv; w2 *= inv;
;     const u32x4 v0 = *(const u32x4*)y, v1 = *(const u32x4*)o12, v2 = *(const u32x4*)(o12 + 512);
;     u32x4 w;
;     w.x = cvt_pk_bf16(w0 * bflo(v0.x) + w1 * bflo(v1.x) + w2 * bflo(v2.x), w0 * bfhi(v0.x) + w1 * bfhi(v1.x) + w2 * bfhi(v2.x));
;     w.y = cvt_pk_bf16(w0 * bflo(v0.y) + w1 * bflo(v1.y) + w2 * bflo(v2.y), w0 * bfhi(v0.y) + w1 * bfhi(v1.y) + w2 * bfhi(v2.y));
;     w.z = cvt_pk_bf16(w0 * bflo(v0.z) + w1 * bflo(v1.z) + w2 * bflo(v2.z), w0 * bfhi(v0.z) + w1 * bfhi(v1.z) + w2 * bfhi(v2.z));
;     w.w = cvt_pk_bf16(w0 * bflo(v0.w) + w1 * bflo(v1.w) + w2 * bflo(v2.w), w0 * bfhi(v0.w) + w1 * bfhi(v1.w) + w2 * bfhi(v2.w));
;     *(u32x4*)y = w;
; }
.Lcmb_b_tailA:
	s_waitcnt vmcnt(3)
	v_max3_f32 v29, v26, v27, v28
	s_waitcnt vmcnt(2)
	v_lshlrev_b32_e32 v32, 16, v7
	v_and_b32_e32 v33, 0xffff0000, v7
	v_lshlrev_b32_e32 v36, 16, v9
	s_waitcnt vmcnt(1)
	v_lshlrev_b32_e32 v7, 16, v10
	v_and_b32_e32 v19, 0xffff0000, v10
	s_waitcnt vmcnt(0)
	v_lshlrev_b32_e32 v20, 16, v15
	v_and_b32_e32 v10, 0xffff0000, v15
	v_lshlrev_b32_e32 v15, 16, v12
	v_and_b32_e32 v23, 0xffff0000, v12
	v_lshlrev_b32_e32 v25, 16, v13
	v_and_b32_e32 v37, 0xffff0000, v9
	v_and_b32_e32 v9, 0xffff0000, v13
	v_sub_f32_e32 v12, v26, v29
	v_sub_f32_e32 v13, v27, v29
	v_lshlrev_b32_e32 v30, 16, v6
	v_and_b32_e32 v31, 0xffff0000, v6
	v_lshlrev_b32_e32 v34, 16, v8
	v_and_b32_e32 v35, 0xffff0000, v8
	v_lshlrev_b32_e32 v6, 16, v14
	v_and_b32_e32 v18, 0xffff0000, v14
	v_lshlrev_b32_e32 v14, 16, v16
	v_and_b32_e32 v22, 0xffff0000, v16
	v_lshlrev_b32_e32 v24, 16, v17
	v_and_b32_e32 v8, 0xffff0000, v17
	v_sub_f32_e32 v16, v28, v29
	v_mul_f32_e32 v12, 0x3fb8aa3b, v12
	v_mul_f32_e32 v17, 0x3fb8aa3b, v13
	v_mul_f32_e32 v16, 0x3fb8aa3b, v16
	v_exp_f32_e32 v13, v12
	v_exp_f32_e32 v17, v17
	v_exp_f32_e32 v12, v16
	v_lshlrev_b32_e32 v21, 16, v11
	v_and_b32_e32 v11, 0xffff0000, v11
	v_add_f32_e32 v16, v13, v17
	v_add_f32_e32 v16, v12, v16
	v_div_scale_f32 v26, s[8:9], v16, v16, 1.0
	v_rcp_f32_e32 v28, v26
	v_div_scale_f32 v27, vcc, 1.0, v16, 1.0
	v_fma_f32 v29, -v26, v28, 1.0
	v_fmac_f32_e32 v28, v29, v28
	v_mul_f32_e32 v29, v27, v28
	v_fma_f32 v38, -v26, v29, v27
	v_fmac_f32_e32 v29, v38, v28
	v_fma_f32 v26, -v26, v29, v27
	v_div_fmas_f32 v26, v26, v28, v29
	v_div_fixup_f32 v16, v26, v16, 1.0
	v_pk_mul_f32 v[12:13], v[12:13], v[16:17] op_sel_hi:[1,0]
	v_mul_f32_e32 v26, v17, v16
	v_pk_mul_f32 v[6:7], v[12:13], v[6:7]
	v_pk_mul_f32 v[16:17], v[12:13], v[18:19]
	v_pk_mul_f32 v[8:9], v[12:13], v[8:9]
	v_pk_mul_f32 v[18:19], v[12:13], v[20:21]
	v_pk_mul_f32 v[10:11], v[12:13], v[10:11]
	v_pk_mul_f32 v[14:15], v[12:13], v[14:15]
	v_pk_mul_f32 v[20:21], v[12:13], v[22:23]
	v_pk_mul_f32 v[22:23], v[12:13], v[24:25]
	v_fma_f32 v7, v26, v30, v7
	v_fma_f32 v12, v26, v31, v17
	v_fma_f32 v9, v26, v37, v9
	v_fma_f32 v13, v26, v32, v19
	v_fma_f32 v11, v26, v33, v11
	v_fma_f32 v15, v26, v34, v15
	v_fma_f32 v17, v26, v35, v21
	v_fma_f32 v19, v26, v36, v23
	v_add_f32_e32 v6, v6, v7
	v_add_f32_e32 v7, v16, v12
	v_add_f32_e32 v9, v8, v9
	v_add_f32_e32 v12, v18, v13
	v_add_f32_e32 v10, v10, v11
	v_add_f32_e32 v11, v14, v15
	v_add_f32_e32 v13, v20, v17
	v_add_f32_e32 v14, v22, v19
	v_cvt_pk_bf16_f32 v6, v6, v7
	v_cvt_pk_bf16_f32 v7, v12, v10
	v_cvt_pk_bf16_f32 v8, v11, v13
	v_cvt_pk_bf16_f32 v9, v14, v9
	global_store_dwordx4 v[250:251], v[6:9], off
	s_branch .Lcmb_b_end
; __device__ __forceinline__ unsigned cvt_pk_bf16(float lo, float hi) { unsigned r; asm volatile("v_cvt_pk_bf16_f32 %0, %1, %2" : "=v"(r) : "v"(lo), "v"(hi)); return r; }
; __device__ __forceinline__ float bflo(unsigned w) { return __uint_as_float(w << 16); }
; __device__ __forceinline__ float bfhi(unsigned w) { return __uint_as_float(w & 0xffff0000u); }
; __device__ __forceinline__ void combine_row(const Args& a, size_t row, int lane) {
;     bf16_t* y = (bf16_t*)a.out + row * YP + 8 * lane; const bf16_t* o12 = (const bf16_t*)((unsigned char*)a.out + DO_O12) + row * 1024 + 8 * lane;
;     const float* lse = (const float*)(a.ws + WS_LSE) + row * 12; const int hh = lane >> 4;
;     const float l0 = lse[hh], l1 = lse[4 + hh], l2 = lse[8 + hh]; const float mx = fmaxf(l0, fmaxf(l1, l2));
;     float w0 = __expf(l0 - mx), w1 = __expf(l1 - mx), w2 = __expf(l2 - mx); const float inv = 1.0f / (w0 + w1 + w2); w0 *= inv; w1 *= inv; w2 *= inv;
;     const u32x4 v0 = *(const u32x4*)y, v1 = *(const u32x4*)o12, v2 = *(const u32x4*)(o12 + 512);
;     u32x4 w;
;     w.x = cvt_pk_bf16(w0 * bflo(v0.x) + w1 * bflo(v1.x) + w2 * bflo(v2.x), w0 * bfhi(v0.x) + w1 * bfhi(v1.x) + w2 * bfhi(v2.x));
;     w.y = cvt_pk_bf16(w0 * bflo(v0.y) + w1 * bflo(v1.y) + w2 * bflo(v2.y), w0 * bfhi(v0.y) + w1 * bfhi(v1.y) + w2 * bfhi(v2.y));
;     w.z = cvt_pk_bf16(w0 * bflo(v0.z) + w1 * bflo(v1.z) + w2 * bflo(v2.z), w0 * bfhi(v0.z) + w1 * bfhi(v1.z) + w2 * bfhi(v2.z));
;     w.w = cvt_pk_bf16(w0 * bflo(v0.w) + w1 * bflo(v1.w) + w2 * bflo(v2.w), w0 * bfhi(v0.w) + w1 * bfhi(v1.w) + w2 * bfhi(v2.w));
;     *(u32x4*)y = w;
; }
; __device__ __forceinline__ void xcd_barrier(const XcdBarrier& b) {
;     asm volatile("s_waitcnt vmcnt(0)" ::: "memory");
;     __syncthreads();
;     if (threadIdx.x == 0) {
;         unsigned* bar = b.bar;
;         __builtin_amdgcn_s_waitcnt(0);
;         unsigned nloc = b.st[0], nx = b.st[1];
;         if (nloc == 0u) { xcd_barrier_complete(bar, b.x, nloc, nx); b.st[0] = nloc; b.st[1] = nx; }
.Lcmb_b_tailB:
	s_waitcnt vmcnt(3)
	v_max3_f32 v235, v232, v233, v234
	s_waitcnt vmcnt(2)
	v_lshlrev_b32_e32 v238, 16, v213
	v_and_b32_e32 v239, 0xffff0000, v213
	v_lshlrev_b32_e32 v244, 16, v215
	s_waitcnt vmcnt(1)
	v_lshlrev_b32_e32 v213, 16, v216
	v_and_b32_e32 v225, 0xffff0000, v216
	s_waitcnt vmcnt(0)
	v_lshlrev_b32_e32 v226, 16, v221
	v_and_b32_e32 v216, 0xffff0000, v221
	v_lshlrev_b32_e32 v221, 16, v218
	v_and_b32_e32 v229, 0xffff0000, v218
	v_lshlrev_b32_e32 v231, 16, v219
	v_and_b32_e32 v245, 0xffff0000, v215
	v_and_b32_e32 v215, 0xffff0000, v219
	v_sub_f32_e32 v218, v232, v235
	v_sub_f32_e32 v219, v233, v235
	v_lshlrev_b32_e32 v236, 16, v212
	v_and_b32_e32 v237, 0xffff0000, v212
	v_lshlrev_b32_e32 v240, 16, v214
	v_and_b32_e32 v241, 0xffff0000, v214
	v_lshlrev_b32_e32 v212, 16, v220
	v_and_b32_e32 v224, 0xffff0000, v220
	v_lshlrev_b32_e32 v220, 16, v222
	v_and_b32_e32 v228, 0xffff0000, v222
	v_lshlrev_b32_e32 v230, 16, v223
	v_and_b32_e32 v214, 0xffff0000, v223
	v_sub_f32_e32 v222, v234, v235
	v_mul_f32_e32 v218, 0x3fb8aa3b, v218
	v_mul_f32_e32 v223, 0x3fb8aa3b, v219
	v_mul_f32_e32 v222, 0x3fb8aa3b, v222
	v_exp_f32_e32 v219, v218
	v_exp_f32_e32 v223, v223
	v_exp_f32_e32 v218, v222
	v_lshlrev_b32_e32 v227, 16, v217
	v_and_b32_e32 v217, 0xffff0000, v217
	v_add_f32_e32 v222, v219, v223
	v_add_f32_e32 v222, v218, v222
	v_div_scale_f32 v232, s[8:9], v222, v222, 1.0
	v_rcp_f32_e32 v234, v232
	v_div_scale_f32 v233, vcc, 1.0, v222, 1.0
	v_fma_f32 v235, -v232, v234, 1.0
	v_fmac_f32_e32 v234, v235, v234
	v_mul_f32_e32 v235, v233, v234
	v_fma_f32 v246, -v232, v235, v233
	v_fmac_f32_e32 v235, v246, v234
	v_fma_f32 v232, -v232, v235, v233
	v_div_fmas_f32 v232, v232, v234, v235
	v_div_fixup_f32 v222, v232, v222, 1.0
	v_pk_mul_f32 v[218:219], v[218:219], v[222:223] op_sel_hi:[1,0]
	v_mul_f32_e32 v232, v223, v222
	v_pk_mul_f32 v[212:213], v[218:219], v[212:213]
	v_pk_mul_f32 v[222:223], v[218:219], v[224:225]
	v_pk_mul_f32 v[214:215], v[218:219], v[214:215]
	v_pk_mul_f32 v[224:225], v[218:219], v[226:227]
	v_pk_mul_f32 v[216:217], v[218:219], v[216:217]
	v_pk_mul_f32 v[220:221], v[218:219], v[220:221]
	v_pk_mul_f32 v[226:227], v[218:219], v[228:229]
	v_pk_mul_f32 v[228:229], v[218:219], v[230:231]
	v_fma_f32 v213, v232, v236, v213
	v_fma_f32 v218, v232, v237, v223
	v_fma_f32 v215, v232, v245, v215
	v_fma_f32 v219, v232, v238, v225
	v_fma_f32 v217, v232, v239, v217
	v_fma_f32 v221, v232, v240, v221
	v_fma_f32 v223, v232, v241, v227
	v_fma_f32 v225, v232, v244, v229
	v_add_f32_e32 v212, v212, v213
	v_add_f32_e32 v213, v222, v218
	v_add_f32_e32 v215, v214, v215
	v_add_f32_e32 v218, v224, v219
	v_add_f32_e32 v216, v216, v217
	v_add_f32_e32 v217, v220, v221
	v_add_f32_e32 v219, v226, v223
	v_add_f32_e32 v220, v228, v225
	v_cvt_pk_bf16_f32 v212, v212, v213
	v_cvt_pk_bf16_f32 v213, v218, v216
	v_cvt_pk_bf16_f32 v214, v217, v219
	v_cvt_pk_bf16_f32 v215, v220, v215
	global_store_dwordx4 v[252:253], v[212:215], off
.Lcmb_b_end:
.LBB0_900:
	s_cmp_gt_u32 s25, 4
	s_cselect_b64 s[0:1], -1, 0
	s_and_b64 s[0:1], s[10:11], s[0:1]
	s_andn2_b64 vcc, exec, s[0:1]
	v_readlane_b32 s75, v242, 37
	s_cbranch_vccnz .LBB0_937
	s_waitcnt vmcnt(0)
	v_cmp_eq_u32_e32 vcc, 0, v144
	s_waitcnt vmcnt(0)
	s_barrier
	s_and_saveexec_b64 s[0:1], vcc
	s_cbranch_execz .LBB0_936
	s_add_i32 s2, 0, 0x23fc0
	v_mov_b32_e32 v0, s2
	s_waitcnt vmcnt(0) expcnt(0) lgkmcnt(0)
	ds_read_b32 v2, v0
	s_add_i32 s2, 0, 0x23fc4
	v_mov_b32_e32 v0, s2
	ds_read_b32 v1, v0
	s_waitcnt lgkmcnt(1)
	v_cmp_ne_u32_e32 vcc, 0, v2
	s_cbranch_vccnz .LBB0_917
	v_readlane_b32 s2, v242, 0
	s_mul_i32 s33, s2, s26
	s_add_u32 s2, s22, 0x10200
	s_addc_u32 s3, s23, 0
	s_add_u32 s4, s22, 0x10400
	s_addc_u32 s5, s23, 0
	s_add_u32 s6, s22, 0x10500
	s_addc_u32 s7, s23, 0
	s_add_u32 s8, s22, 0x10600
	s_addc_u32 s9, s23, 0
	s_add_u32 s10, s22, 0x10700
	s_addc_u32 s11, s23, 0
	s_add_u32 s12, s22, 0x10800
	s_addc_u32 s13, s23, 0
	s_add_u32 s14, s22, 0x10900
	s_addc_u32 s15, s23, 0
	s_add_u32 s16, s22, 0x10a00
	s_addc_u32 s17, s23, 0
	s_add_u32 s18, s22, 0x10b00
	s_addc_u32 s19, s23, 0
	s_add_u32 s28, s22, 0x10c00
	s_addc_u32 s29, s23, 0
	s_add_u32 s30, s22, 0x10d00
	s_addc_u32 s31, s23, 0
	s_add_u32 s34, s22, 0x10e00
	s_addc_u32 s35, s23, 0
	s_add_u32 s36, s22, 0x10f00
	s_addc_u32 s37, s23, 0
	s_add_u32 s38, s22, 0x11000
	s_addc_u32 s39, s23, 0
	s_add_u32 s40, s22, 0x11100
	s_addc_u32 s41, s23, 0
	s_add_u32 s42, s22, 0x11200
	s_addc_u32 s43, s23, 0
	s_add_u32 s44, s22, 0x11300
	s_mul_i32 s33, s33, s27
	s_addc_u32 s45, s23, 0
	s_mov_b32 s52, 1
	v_mov_b32_e32 v16, 0
	s_branch .LBB0_905
